# P8 tail task: eight rows per trip (two trips per 128-row chunk)
# speedup vs baseline: 1.0096x; 1.0096x over previous
.Lt8i3_1251:
	s_or_b64 exec, exec, s[40:41]
	s_add_u32 s36, s8, s36
	s_addc_u32 s37, s9, s37
	s_lshl_b64 s[34:35], s[34:35], 10
	s_add_u32 s34, s36, s34
	s_addc_u32 s35, s37, s35
	s_lshl_b64 s[36:37], s[16:17], 2
	s_add_u32 s36, s42, s36
	s_addc_u32 s37, s43, s37
	global_load_dword v68, v1, s[36:37]
	s_add_i32 s16, s47, s48
	s_add_i32 s16, s16, 32
	s_cmpk_gt_u32 s16, 0xffff
	s_mov_b64 s[30:31], -1
	s_cbranch_scc0 .Lt8i4_1246
	s_add_i32 s34, s16, 0xffff0000
	s_lshr_b32 s11, s34, 5
	s_and_b32 s10, s16, 31
	s_mul_hi_u32 s28, s11, 0x840
	s_mulk_i32 s11, 0x840
	s_or_b32 s49, s10, 0x800
	s_or_b32 s10, s11, s10
	s_add_u32 s10, s10, 0x10800
	s_mov_b32 s35, s17
	s_addc_u32 s11, s28, 0
	s_lshl_b64 s[28:29], s[34:35], 7
	s_mov_b64 s[30:31], 0

.Lt8i4_1249:
	s_lshl_b64 s[40:41], s[10:11], 9
	s_waitcnt lgkmcnt(0)
	v_lshl_add_u64 v[70:71], v[2:3], 0, s[40:41]
	global_load_dwordx2 v[70:71], v[70:71], off
	v_mov_b32_e32 v0, 0
	v_mov_b32_e32 v72, 0
	v_mov_b32_e32 v73, 0
	s_and_saveexec_b64 s[40:41], s[4:5]
	s_cbranch_execz .Lt8i4_1251
	v_lshl_add_u64 v[32:33], v[4:5], 0, s[38:39]
	global_load_dword v72, v[32:33], off
	global_load_dword v73, v[6:7], off
	v_lshl_or_b32 v42, s49, 5, v12
	v_mov_b32_e32 v43, 0
	v_lshl_add_u64 v[44:45], v[42:43], 2, s[18:19]
	global_load_dword v74, v[44:45], off offset:64
	global_load_dword v75, v[44:45], off
.Lt8i4_1251:
	s_or_b64 exec, exec, s[40:41]
	s_add_u32 s36, s8, s36
	s_addc_u32 s37, s9, s37
	s_lshl_b64 s[34:35], s[34:35], 10
	s_add_u32 s34, s36, s34
	s_addc_u32 s35, s37, s35
	s_lshl_b64 s[36:37], s[16:17], 2
	s_add_u32 s36, s42, s36
	s_addc_u32 s37, s43, s37
	global_load_dword v76, v1, s[36:37]
	s_add_i32 s16, s47, s48
	s_add_i32 s16, s16, 40
	s_cmpk_gt_u32 s16, 0xffff
	s_mov_b64 s[30:31], -1
	s_cbranch_scc0 .Lt8i5_1246
	s_add_i32 s34, s16, 0xffff0000
	s_lshr_b32 s11, s34, 5
	s_and_b32 s10, s16, 31
	s_mul_hi_u32 s28, s11, 0x840
	s_mulk_i32 s11, 0x840
	s_or_b32 s49, s10, 0x800
	s_or_b32 s10, s11, s10
	s_add_u32 s10, s10, 0x10800
	s_mov_b32 s35, s17
	s_addc_u32 s11, s28, 0
	s_lshl_b64 s[28:29], s[34:35], 7
	s_mov_b64 s[30:31], 0

.Lt8i5_1249:
	s_lshl_b64 s[40:41], s[10:11], 9
	s_waitcnt lgkmcnt(0)
	v_lshl_add_u64 v[78:79], v[2:3], 0, s[40:41]
	global_load_dwordx2 v[78:79], v[78:79], off
	v_mov_b32_e32 v0, 0
	v_mov_b32_e32 v80, 0
	v_mov_b32_e32 v81, 0
	s_and_saveexec_b64 s[40:41], s[4:5]
	s_cbranch_execz .Lt8i5_1251
	v_lshl_add_u64 v[32:33], v[4:5], 0, s[38:39]
	global_load_dword v80, v[32:33], off
	global_load_dword v81, v[6:7], off
	v_lshl_or_b32 v42, s49, 5, v12
	v_mov_b32_e32 v43, 0
	v_lshl_add_u64 v[44:45], v[42:43], 2, s[18:19]
	global_load_dword v82, v[44:45], off offset:64
	global_load_dword v83, v[44:45], off
.Lt8i5_1251:
	s_or_b64 exec, exec, s[40:41]
	s_add_u32 s36, s8, s36
	s_addc_u32 s37, s9, s37
	s_lshl_b64 s[34:35], s[34:35], 10
	s_add_u32 s34, s36, s34
	s_addc_u32 s35, s37, s35
	s_lshl_b64 s[36:37], s[16:17], 2
	s_add_u32 s36, s42, s36
	s_addc_u32 s37, s43, s37
	global_load_dword v84, v1, s[36:37]
	s_add_i32 s16, s47, s48
	s_add_i32 s16, s16, 48
	s_cmpk_gt_u32 s16, 0xffff
	s_mov_b64 s[30:31], -1
	s_cbranch_scc0 .Lt8i6_1246
	s_add_i32 s34, s16, 0xffff0000
	s_lshr_b32 s11, s34, 5
	s_and_b32 s10, s16, 31
	s_mul_hi_u32 s28, s11, 0x840
	s_mulk_i32 s11, 0x840
	s_or_b32 s49, s10, 0x800
	s_or_b32 s10, s11, s10
	s_add_u32 s10, s10, 0x10800
	s_mov_b32 s35, s17
	s_addc_u32 s11, s28, 0
	s_lshl_b64 s[28:29], s[34:35], 7
	s_mov_b64 s[30:31], 0

.Lt8i6_1249:
	s_lshl_b64 s[40:41], s[10:11], 9
	s_waitcnt lgkmcnt(0)
	v_lshl_add_u64 v[86:87], v[2:3], 0, s[40:41]
	global_load_dwordx2 v[86:87], v[86:87], off
	v_mov_b32_e32 v0, 0
	v_mov_b32_e32 v88, 0
	v_mov_b32_e32 v89, 0
	s_and_saveexec_b64 s[40:41], s[4:5]
	s_cbranch_execz .Lt8i6_1251
	v_lshl_add_u64 v[32:33], v[4:5], 0, s[38:39]
	global_load_dword v88, v[32:33], off
	global_load_dword v89, v[6:7], off
	v_lshl_or_b32 v42, s49, 5, v12
	v_mov_b32_e32 v43, 0
	v_lshl_add_u64 v[44:45], v[42:43], 2, s[18:19]
	global_load_dword v90, v[44:45], off offset:64
	global_load_dword v91, v[44:45], off
.Lt8i6_1251:
	s_or_b64 exec, exec, s[40:41]
	s_add_u32 s36, s8, s36
	s_addc_u32 s37, s9, s37
	s_lshl_b64 s[34:35], s[34:35], 10
	s_add_u32 s34, s36, s34
	s_addc_u32 s35, s37, s35
	s_lshl_b64 s[36:37], s[16:17], 2
	s_add_u32 s36, s42, s36
	s_addc_u32 s37, s43, s37
	global_load_dword v92, v1, s[36:37]
	s_add_i32 s16, s47, s48
	s_add_i32 s16, s16, 56
	s_cmpk_gt_u32 s16, 0xffff
	s_mov_b64 s[30:31], -1
	s_cbranch_scc0 .Lt8i7_1246
	s_add_i32 s34, s16, 0xffff0000
	s_lshr_b32 s11, s34, 5
	s_and_b32 s10, s16, 31
	s_mul_hi_u32 s28, s11, 0x840
	s_mulk_i32 s11, 0x840
	s_or_b32 s49, s10, 0x800
	s_or_b32 s10, s11, s10
	s_add_u32 s10, s10, 0x10800
	s_mov_b32 s35, s17
	s_addc_u32 s11, s28, 0
	s_lshl_b64 s[28:29], s[34:35], 7
	s_mov_b64 s[30:31], 0

.Lt8i7_1249:
	s_lshl_b64 s[40:41], s[10:11], 9
	s_waitcnt lgkmcnt(0)
	v_lshl_add_u64 v[94:95], v[2:3], 0, s[40:41]
	global_load_dwordx2 v[94:95], v[94:95], off
	v_mov_b32_e32 v0, 0
	v_mov_b32_e32 v96, 0
	v_mov_b32_e32 v97, 0
	s_and_saveexec_b64 s[40:41], s[4:5]
	s_cbranch_execz .Lt8i7_1251
	v_lshl_add_u64 v[32:33], v[4:5], 0, s[38:39]
	global_load_dword v96, v[32:33], off
	global_load_dword v97, v[6:7], off
	v_lshl_or_b32 v42, s49, 5, v12
	v_mov_b32_e32 v43, 0
	v_lshl_add_u64 v[44:45], v[42:43], 2, s[18:19]
	global_load_dword v98, v[44:45], off offset:64
	global_load_dword v99, v[44:45], off
.Lt8i7_1251:
	s_or_b64 exec, exec, s[40:41]
	s_add_u32 s36, s8, s36
	s_addc_u32 s37, s9, s37
	s_lshl_b64 s[34:35], s[34:35], 10
	s_add_u32 s34, s36, s34
	s_addc_u32 s35, s37, s35
	s_lshl_b64 s[36:37], s[16:17], 2
	s_add_u32 s36, s42, s36
	s_addc_u32 s37, s43, s37
	global_load_dword v100, v1, s[36:37]
	s_add_i32 s16, s47, s48
	s_cmpk_gt_u32 s16, 0xffff
	s_mov_b64 s[30:31], -1
	s_cbranch_scc0 .Lt8r0_1246
	s_add_i32 s34, s16, 0xffff0000
	s_lshr_b32 s11, s34, 5
	s_and_b32 s10, s16, 31
	s_mul_hi_u32 s28, s11, 0x840
	s_mulk_i32 s11, 0x840
	s_or_b32 s49, s10, 0x800
	s_or_b32 s10, s11, s10
	s_add_u32 s10, s10, 0x10800
	s_mov_b32 s35, s17
	s_addc_u32 s11, s28, 0
	s_lshl_b64 s[28:29], s[34:35], 7
	s_mov_b64 s[30:31], 0

.Lt8r0_1251:
	s_add_u32 s36, s8, s36
	s_addc_u32 s37, s9, s37
	s_lshl_b64 s[34:35], s[34:35], 10
	s_add_u32 s34, s36, s34
	s_addc_u32 s35, s37, s35
	s_lshl_b64 s[36:37], s[16:17], 2
	s_add_u32 s36, s42, s36
	s_addc_u32 s37, s43, s37
	s_waitcnt vmcnt(46)
	v_mul_f32_e32 v36, v31, v31
	v_lshlrev_b32_e32 v34, 16, v11
	v_lshlrev_b32_e32 v32, 16, v10
	v_and_b32_e32 v33, 0xffff0000, v10
	v_add_f32_dpp v36, v36, v36 quad_perm:[1,0,3,2] row_mask:0xf bank_mask:0xf
	s_nop 1
	v_add_f32_dpp v36, v36, v36 quad_perm:[2,3,0,1] row_mask:0xf bank_mask:0xf
	s_nop 1
	v_add_f32_dpp v36, v36, v36 row_half_mirror row_mask:0xf bank_mask:0xf
	s_nop 1
	v_add_f32_dpp v36, v36, v36 row_mirror row_mask:0xf bank_mask:0xf
	ds_bpermute_b32 v37, v29, v36
	s_waitcnt lgkmcnt(0)
	v_add_f32_e32 v10, v36, v37
	s_waitcnt vmcnt(42)
	v_fmamk_f32 v35, v35, 0x3b800000, v14
	v_mul_f32_e32 v37, 0x4b800000, v35
	v_cmp_gt_f32_e32 vcc, s46, v35
	s_nop 1
	v_cndmask_b32_e32 v35, v35, v37, vcc
	v_rsq_f32_e32 v37, v35
	v_and_b32_e32 v35, 0xffff0000, v11
	v_mul_f32_e32 v36, 0x45800000, v37
	v_cndmask_b32_e32 v36, v37, v36, vcc
	v_pk_mul_f32 v[34:35], v[36:37], v[34:35] op_sel_hi:[0,1]
	v_pk_mul_f32 v[32:33], v[36:37], v[32:33] op_sel_hi:[0,1]
	global_store_dwordx4 v15, v[32:35], s[34:35] nt
	v_fmamk_f32 v10, v10, 0x3d000000, v14
	v_mul_f32_e32 v11, 0x4b800000, v10
	v_cmp_gt_f32_e32 vcc, s46, v10
	s_nop 1
	v_cndmask_b32_e32 v10, v10, v11, vcc
	v_rsq_f32_e32 v10, v10
	s_nop 0
	v_mul_f32_e32 v11, 0x45800000, v10
	v_cndmask_b32_e32 v10, v10, v11, vcc
	v_mul_f32_e32 v10, v31, v10
	s_waitcnt vmcnt(43)
	v_mul_f32_e32 v10, v10, v38
	ds_bpermute_b32 v11, v29, v10
	s_and_saveexec_b64 s[34:35], s[4:5]
	s_cbranch_execz .Lt8_end0
	s_add_u32 s16, s8, s30
	s_addc_u32 s30, s9, s31
	s_add_u32 s28, s16, s28
	s_addc_u32 s29, s30, s29
	s_lshl_b64 s[10:11], s[10:11], 6
	s_waitcnt vmcnt(43) lgkmcnt(0)
	v_mul_f32_e32 v0, v39, v11
	v_cndmask_b32_e64 v0, v0, -v0, s[6:7]
	s_waitcnt vmcnt(43)
	v_fmac_f32_e32 v0, v10, v40
	global_store_dword v16, v0, s[28:29]
	v_cvt_pk_bf16_f32 v0, v0, s0
	v_lshl_add_u64 v[10:11], v[8:9], 0, s[10:11]
	global_store_short v[10:11], v0, off

.Lt8r1_1251:
	s_add_u32 s36, s8, s36
	s_addc_u32 s37, s9, s37
	s_lshl_b64 s[34:35], s[34:35], 10
	s_add_u32 s34, s36, s34
	s_addc_u32 s35, s37, s35
	s_lshl_b64 s[36:37], s[16:17], 2
	s_add_u32 s36, s42, s36
	s_addc_u32 s37, s43, s37
	s_waitcnt vmcnt(43)
	v_mul_f32_e32 v36, v48, v48
	v_lshlrev_b32_e32 v34, 16, v47
	v_lshlrev_b32_e32 v32, 16, v46
	v_and_b32_e32 v33, 0xffff0000, v46
	v_add_f32_dpp v36, v36, v36 quad_perm:[1,0,3,2] row_mask:0xf bank_mask:0xf
	s_nop 1
	v_add_f32_dpp v36, v36, v36 quad_perm:[2,3,0,1] row_mask:0xf bank_mask:0xf
	s_nop 1
	v_add_f32_dpp v36, v36, v36 row_half_mirror row_mask:0xf bank_mask:0xf
	s_nop 1
	v_add_f32_dpp v36, v36, v36 row_mirror row_mask:0xf bank_mask:0xf
	ds_bpermute_b32 v37, v29, v36
	s_waitcnt lgkmcnt(0)
	v_add_f32_e32 v46, v36, v37
	s_waitcnt vmcnt(39)
	v_fmamk_f32 v35, v52, 0x3b800000, v14
	v_mul_f32_e32 v37, 0x4b800000, v35
	v_cmp_gt_f32_e32 vcc, s46, v35
	s_nop 1
	v_cndmask_b32_e32 v35, v35, v37, vcc
	v_rsq_f32_e32 v37, v35
	v_and_b32_e32 v35, 0xffff0000, v47
	v_mul_f32_e32 v36, 0x45800000, v37
	v_cndmask_b32_e32 v36, v37, v36, vcc
	v_pk_mul_f32 v[34:35], v[36:37], v[34:35] op_sel_hi:[0,1]
	v_pk_mul_f32 v[32:33], v[36:37], v[32:33] op_sel_hi:[0,1]
	global_store_dwordx4 v15, v[32:35], s[34:35] nt
	v_fmamk_f32 v46, v46, 0x3d000000, v14
	v_mul_f32_e32 v47, 0x4b800000, v46
	v_cmp_gt_f32_e32 vcc, s46, v46
	s_nop 1
	v_cndmask_b32_e32 v46, v46, v47, vcc
	v_rsq_f32_e32 v46, v46
	s_nop 0
	v_mul_f32_e32 v47, 0x45800000, v46
	v_cndmask_b32_e32 v46, v46, v47, vcc
	v_mul_f32_e32 v46, v48, v46
	s_waitcnt vmcnt(40)
	v_mul_f32_e32 v46, v46, v49
	ds_bpermute_b32 v47, v29, v46
	s_and_saveexec_b64 s[34:35], s[4:5]
	s_cbranch_execz .Lt8_end1
	s_add_u32 s16, s8, s30
	s_addc_u32 s30, s9, s31
	s_add_u32 s28, s16, s28
	s_addc_u32 s29, s30, s29
	s_lshl_b64 s[10:11], s[10:11], 6
	s_waitcnt vmcnt(40) lgkmcnt(0)
	v_mul_f32_e32 v0, v50, v47
	v_cndmask_b32_e64 v0, v0, -v0, s[6:7]
	s_waitcnt vmcnt(40)
	v_fmac_f32_e32 v0, v46, v51
	global_store_dword v16, v0, s[28:29]
	v_cvt_pk_bf16_f32 v0, v0, s0
	v_lshl_add_u64 v[46:47], v[8:9], 0, s[10:11]
	global_store_short v[46:47], v0, off

.Lt8r2_1251:
	s_add_u32 s36, s8, s36
	s_addc_u32 s37, s9, s37
	s_lshl_b64 s[34:35], s[34:35], 10
	s_add_u32 s34, s36, s34
	s_addc_u32 s35, s37, s35
	s_lshl_b64 s[36:37], s[16:17], 2
	s_add_u32 s36, s42, s36
	s_addc_u32 s37, s43, s37
	s_waitcnt vmcnt(40)
	v_mul_f32_e32 v36, v56, v56
	v_lshlrev_b32_e32 v34, 16, v55
	v_lshlrev_b32_e32 v32, 16, v54
	v_and_b32_e32 v33, 0xffff0000, v54
	v_add_f32_dpp v36, v36, v36 quad_perm:[1,0,3,2] row_mask:0xf bank_mask:0xf
	s_nop 1
	v_add_f32_dpp v36, v36, v36 quad_perm:[2,3,0,1] row_mask:0xf bank_mask:0xf
	s_nop 1
	v_add_f32_dpp v36, v36, v36 row_half_mirror row_mask:0xf bank_mask:0xf
	s_nop 1
	v_add_f32_dpp v36, v36, v36 row_mirror row_mask:0xf bank_mask:0xf
	ds_bpermute_b32 v37, v29, v36
	s_waitcnt lgkmcnt(0)
	v_add_f32_e32 v54, v36, v37
	s_waitcnt vmcnt(36)
	v_fmamk_f32 v35, v60, 0x3b800000, v14
	v_mul_f32_e32 v37, 0x4b800000, v35
	v_cmp_gt_f32_e32 vcc, s46, v35
	s_nop 1
	v_cndmask_b32_e32 v35, v35, v37, vcc
	v_rsq_f32_e32 v37, v35
	v_and_b32_e32 v35, 0xffff0000, v55
	v_mul_f32_e32 v36, 0x45800000, v37
	v_cndmask_b32_e32 v36, v37, v36, vcc
	v_pk_mul_f32 v[34:35], v[36:37], v[34:35] op_sel_hi:[0,1]
	v_pk_mul_f32 v[32:33], v[36:37], v[32:33] op_sel_hi:[0,1]
	global_store_dwordx4 v15, v[32:35], s[34:35] nt
	v_fmamk_f32 v54, v54, 0x3d000000, v14
	v_mul_f32_e32 v55, 0x4b800000, v54
	v_cmp_gt_f32_e32 vcc, s46, v54
	s_nop 1
	v_cndmask_b32_e32 v54, v54, v55, vcc
	v_rsq_f32_e32 v54, v54
	s_nop 0
	v_mul_f32_e32 v55, 0x45800000, v54
	v_cndmask_b32_e32 v54, v54, v55, vcc
	v_mul_f32_e32 v54, v56, v54
	s_waitcnt vmcnt(37)
	v_mul_f32_e32 v54, v54, v57
	ds_bpermute_b32 v55, v29, v54
	s_and_saveexec_b64 s[34:35], s[4:5]
	s_cbranch_execz .Lt8_end2
	s_add_u32 s16, s8, s30
	s_addc_u32 s30, s9, s31
	s_add_u32 s28, s16, s28
	s_addc_u32 s29, s30, s29
	s_lshl_b64 s[10:11], s[10:11], 6
	s_waitcnt vmcnt(37) lgkmcnt(0)
	v_mul_f32_e32 v0, v58, v55
	v_cndmask_b32_e64 v0, v0, -v0, s[6:7]
	s_waitcnt vmcnt(37)
	v_fmac_f32_e32 v0, v54, v59
	global_store_dword v16, v0, s[28:29]
	v_cvt_pk_bf16_f32 v0, v0, s0
	v_lshl_add_u64 v[54:55], v[8:9], 0, s[10:11]
	global_store_short v[54:55], v0, off

.Lt8r3_1251:
	s_add_u32 s36, s8, s36
	s_addc_u32 s37, s9, s37
	s_lshl_b64 s[34:35], s[34:35], 10
	s_add_u32 s34, s36, s34
	s_addc_u32 s35, s37, s35
	s_lshl_b64 s[36:37], s[16:17], 2
	s_add_u32 s36, s42, s36
	s_addc_u32 s37, s43, s37
	s_waitcnt vmcnt(37)
	v_mul_f32_e32 v36, v64, v64
	v_lshlrev_b32_e32 v34, 16, v63
	v_lshlrev_b32_e32 v32, 16, v62
	v_and_b32_e32 v33, 0xffff0000, v62
	v_add_f32_dpp v36, v36, v36 quad_perm:[1,0,3,2] row_mask:0xf bank_mask:0xf
	s_nop 1
	v_add_f32_dpp v36, v36, v36 quad_perm:[2,3,0,1] row_mask:0xf bank_mask:0xf
	s_nop 1
	v_add_f32_dpp v36, v36, v36 row_half_mirror row_mask:0xf bank_mask:0xf
	s_nop 1
	v_add_f32_dpp v36, v36, v36 row_mirror row_mask:0xf bank_mask:0xf
	ds_bpermute_b32 v37, v29, v36
	s_waitcnt lgkmcnt(0)
	v_add_f32_e32 v62, v36, v37
	s_waitcnt vmcnt(33)
	v_fmamk_f32 v35, v68, 0x3b800000, v14
	v_mul_f32_e32 v37, 0x4b800000, v35
	v_cmp_gt_f32_e32 vcc, s46, v35
	s_nop 1
	v_cndmask_b32_e32 v35, v35, v37, vcc
	v_rsq_f32_e32 v37, v35
	v_and_b32_e32 v35, 0xffff0000, v63
	v_mul_f32_e32 v36, 0x45800000, v37
	v_cndmask_b32_e32 v36, v37, v36, vcc
	v_pk_mul_f32 v[34:35], v[36:37], v[34:35] op_sel_hi:[0,1]
	v_pk_mul_f32 v[32:33], v[36:37], v[32:33] op_sel_hi:[0,1]
	global_store_dwordx4 v15, v[32:35], s[34:35] nt
	v_fmamk_f32 v62, v62, 0x3d000000, v14
	v_mul_f32_e32 v63, 0x4b800000, v62
	v_cmp_gt_f32_e32 vcc, s46, v62
	s_nop 1
	v_cndmask_b32_e32 v62, v62, v63, vcc
	v_rsq_f32_e32 v62, v62
	s_nop 0
	v_mul_f32_e32 v63, 0x45800000, v62
	v_cndmask_b32_e32 v62, v62, v63, vcc
	v_mul_f32_e32 v62, v64, v62
	s_waitcnt vmcnt(34)
	v_mul_f32_e32 v62, v62, v65
	ds_bpermute_b32 v63, v29, v62
	s_and_saveexec_b64 s[34:35], s[4:5]
	s_cbranch_execz .Lt8_end3
	s_add_u32 s16, s8, s30
	s_addc_u32 s30, s9, s31
	s_add_u32 s28, s16, s28
	s_addc_u32 s29, s30, s29
	s_lshl_b64 s[10:11], s[10:11], 6
	s_waitcnt vmcnt(34) lgkmcnt(0)
	v_mul_f32_e32 v0, v66, v63
	v_cndmask_b32_e64 v0, v0, -v0, s[6:7]
	s_waitcnt vmcnt(34)
	v_fmac_f32_e32 v0, v62, v67
	global_store_dword v16, v0, s[28:29]
	v_cvt_pk_bf16_f32 v0, v0, s0
	v_lshl_add_u64 v[62:63], v[8:9], 0, s[10:11]
	global_store_short v[62:63], v0, off
.Lt8_end3:
	s_or_b64 exec, exec, s[34:35]
	s_add_i32 s16, s47, s48
	s_add_i32 s16, s16, 32
	s_cmpk_gt_u32 s16, 0xffff
	s_mov_b64 s[30:31], -1
	s_cbranch_scc0 .Lt8r4_1246
	s_add_i32 s34, s16, 0xffff0000
	s_lshr_b32 s11, s34, 5
	s_and_b32 s10, s16, 31
	s_mul_hi_u32 s28, s11, 0x840
	s_mulk_i32 s11, 0x840
	s_or_b32 s49, s10, 0x800
	s_or_b32 s10, s11, s10
	s_add_u32 s10, s10, 0x10800
	s_mov_b32 s35, s17
	s_addc_u32 s11, s28, 0
	s_lshl_b64 s[28:29], s[34:35], 7
	s_mov_b64 s[30:31], 0

.Lt8r4_1251:
	s_add_u32 s36, s8, s36
	s_addc_u32 s37, s9, s37
	s_lshl_b64 s[34:35], s[34:35], 10
	s_add_u32 s34, s36, s34
	s_addc_u32 s35, s37, s35
	s_lshl_b64 s[36:37], s[16:17], 2
	s_add_u32 s36, s42, s36
	s_addc_u32 s37, s43, s37
	s_waitcnt vmcnt(34)
	v_mul_f32_e32 v36, v72, v72
	v_lshlrev_b32_e32 v34, 16, v71
	v_lshlrev_b32_e32 v32, 16, v70
	v_and_b32_e32 v33, 0xffff0000, v70
	v_add_f32_dpp v36, v36, v36 quad_perm:[1,0,3,2] row_mask:0xf bank_mask:0xf
	s_nop 1
	v_add_f32_dpp v36, v36, v36 quad_perm:[2,3,0,1] row_mask:0xf bank_mask:0xf
	s_nop 1
	v_add_f32_dpp v36, v36, v36 row_half_mirror row_mask:0xf bank_mask:0xf
	s_nop 1
	v_add_f32_dpp v36, v36, v36 row_mirror row_mask:0xf bank_mask:0xf
	ds_bpermute_b32 v37, v29, v36
	s_waitcnt lgkmcnt(0)
	v_add_f32_e32 v70, v36, v37
	s_waitcnt vmcnt(30)
	v_fmamk_f32 v35, v76, 0x3b800000, v14
	v_mul_f32_e32 v37, 0x4b800000, v35
	v_cmp_gt_f32_e32 vcc, s46, v35
	s_nop 1
	v_cndmask_b32_e32 v35, v35, v37, vcc
	v_rsq_f32_e32 v37, v35
	v_and_b32_e32 v35, 0xffff0000, v71
	v_mul_f32_e32 v36, 0x45800000, v37
	v_cndmask_b32_e32 v36, v37, v36, vcc
	v_pk_mul_f32 v[34:35], v[36:37], v[34:35] op_sel_hi:[0,1]
	v_pk_mul_f32 v[32:33], v[36:37], v[32:33] op_sel_hi:[0,1]
	global_store_dwordx4 v15, v[32:35], s[34:35] nt
	v_fmamk_f32 v70, v70, 0x3d000000, v14
	v_mul_f32_e32 v71, 0x4b800000, v70
	v_cmp_gt_f32_e32 vcc, s46, v70
	s_nop 1
	v_cndmask_b32_e32 v70, v70, v71, vcc
	v_rsq_f32_e32 v70, v70
	s_nop 0
	v_mul_f32_e32 v71, 0x45800000, v70
	v_cndmask_b32_e32 v70, v70, v71, vcc
	v_mul_f32_e32 v70, v72, v70
	s_waitcnt vmcnt(31)
	v_mul_f32_e32 v70, v70, v73
	ds_bpermute_b32 v71, v29, v70
	s_and_saveexec_b64 s[34:35], s[4:5]
	s_cbranch_execz .Lt8_end4
	s_add_u32 s16, s8, s30
	s_addc_u32 s30, s9, s31
	s_add_u32 s28, s16, s28
	s_addc_u32 s29, s30, s29
	s_lshl_b64 s[10:11], s[10:11], 6
	s_waitcnt vmcnt(31) lgkmcnt(0)
	v_mul_f32_e32 v0, v74, v71
	v_cndmask_b32_e64 v0, v0, -v0, s[6:7]
	s_waitcnt vmcnt(31)
	v_fmac_f32_e32 v0, v70, v75
	global_store_dword v16, v0, s[28:29]
	v_cvt_pk_bf16_f32 v0, v0, s0
	v_lshl_add_u64 v[70:71], v[8:9], 0, s[10:11]
	global_store_short v[70:71], v0, off
.Lt8_end4:
	s_or_b64 exec, exec, s[34:35]
	s_add_i32 s16, s47, s48
	s_add_i32 s16, s16, 40
	s_cmpk_gt_u32 s16, 0xffff
	s_mov_b64 s[30:31], -1
	s_cbranch_scc0 .Lt8r5_1246
	s_add_i32 s34, s16, 0xffff0000
	s_lshr_b32 s11, s34, 5
	s_and_b32 s10, s16, 31
	s_mul_hi_u32 s28, s11, 0x840
	s_mulk_i32 s11, 0x840
	s_or_b32 s49, s10, 0x800
	s_or_b32 s10, s11, s10
	s_add_u32 s10, s10, 0x10800
	s_mov_b32 s35, s17
	s_addc_u32 s11, s28, 0
	s_lshl_b64 s[28:29], s[34:35], 7
	s_mov_b64 s[30:31], 0

.Lt8r5_1251:
	s_add_u32 s36, s8, s36
	s_addc_u32 s37, s9, s37
	s_lshl_b64 s[34:35], s[34:35], 10
	s_add_u32 s34, s36, s34
	s_addc_u32 s35, s37, s35
	s_lshl_b64 s[36:37], s[16:17], 2
	s_add_u32 s36, s42, s36
	s_addc_u32 s37, s43, s37
	s_waitcnt vmcnt(31)
	v_mul_f32_e32 v36, v80, v80
	v_lshlrev_b32_e32 v34, 16, v79
	v_lshlrev_b32_e32 v32, 16, v78
	v_and_b32_e32 v33, 0xffff0000, v78
	v_add_f32_dpp v36, v36, v36 quad_perm:[1,0,3,2] row_mask:0xf bank_mask:0xf
	s_nop 1
	v_add_f32_dpp v36, v36, v36 quad_perm:[2,3,0,1] row_mask:0xf bank_mask:0xf
	s_nop 1
	v_add_f32_dpp v36, v36, v36 row_half_mirror row_mask:0xf bank_mask:0xf
	s_nop 1
	v_add_f32_dpp v36, v36, v36 row_mirror row_mask:0xf bank_mask:0xf
	ds_bpermute_b32 v37, v29, v36
	s_waitcnt lgkmcnt(0)
	v_add_f32_e32 v78, v36, v37
	s_waitcnt vmcnt(27)
	v_fmamk_f32 v35, v84, 0x3b800000, v14
	v_mul_f32_e32 v37, 0x4b800000, v35
	v_cmp_gt_f32_e32 vcc, s46, v35
	s_nop 1
	v_cndmask_b32_e32 v35, v35, v37, vcc
	v_rsq_f32_e32 v37, v35
	v_and_b32_e32 v35, 0xffff0000, v79
	v_mul_f32_e32 v36, 0x45800000, v37
	v_cndmask_b32_e32 v36, v37, v36, vcc
	v_pk_mul_f32 v[34:35], v[36:37], v[34:35] op_sel_hi:[0,1]
	v_pk_mul_f32 v[32:33], v[36:37], v[32:33] op_sel_hi:[0,1]
	global_store_dwordx4 v15, v[32:35], s[34:35] nt
	v_fmamk_f32 v78, v78, 0x3d000000, v14
	v_mul_f32_e32 v79, 0x4b800000, v78
	v_cmp_gt_f32_e32 vcc, s46, v78
	s_nop 1
	v_cndmask_b32_e32 v78, v78, v79, vcc
	v_rsq_f32_e32 v78, v78
	s_nop 0
	v_mul_f32_e32 v79, 0x45800000, v78
	v_cndmask_b32_e32 v78, v78, v79, vcc
	v_mul_f32_e32 v78, v80, v78
	s_waitcnt vmcnt(28)
	v_mul_f32_e32 v78, v78, v81
	ds_bpermute_b32 v79, v29, v78
	s_and_saveexec_b64 s[34:35], s[4:5]
	s_cbranch_execz .Lt8_end5
	s_add_u32 s16, s8, s30
	s_addc_u32 s30, s9, s31
	s_add_u32 s28, s16, s28
	s_addc_u32 s29, s30, s29
	s_lshl_b64 s[10:11], s[10:11], 6
	s_waitcnt vmcnt(28) lgkmcnt(0)
	v_mul_f32_e32 v0, v82, v79
	v_cndmask_b32_e64 v0, v0, -v0, s[6:7]
	s_waitcnt vmcnt(28)
	v_fmac_f32_e32 v0, v78, v83
	global_store_dword v16, v0, s[28:29]
	v_cvt_pk_bf16_f32 v0, v0, s0
	v_lshl_add_u64 v[78:79], v[8:9], 0, s[10:11]
	global_store_short v[78:79], v0, off
.Lt8_end5:
	s_or_b64 exec, exec, s[34:35]
	s_add_i32 s16, s47, s48
	s_add_i32 s16, s16, 48
	s_cmpk_gt_u32 s16, 0xffff
	s_mov_b64 s[30:31], -1
	s_cbranch_scc0 .Lt8r6_1246
	s_add_i32 s34, s16, 0xffff0000
	s_lshr_b32 s11, s34, 5
	s_and_b32 s10, s16, 31
	s_mul_hi_u32 s28, s11, 0x840
	s_mulk_i32 s11, 0x840
	s_or_b32 s49, s10, 0x800
	s_or_b32 s10, s11, s10
	s_add_u32 s10, s10, 0x10800
	s_mov_b32 s35, s17
	s_addc_u32 s11, s28, 0
	s_lshl_b64 s[28:29], s[34:35], 7
	s_mov_b64 s[30:31], 0

.Lt8r6_1251:
	s_add_u32 s36, s8, s36
	s_addc_u32 s37, s9, s37
	s_lshl_b64 s[34:35], s[34:35], 10
	s_add_u32 s34, s36, s34
	s_addc_u32 s35, s37, s35
	s_lshl_b64 s[36:37], s[16:17], 2
	s_add_u32 s36, s42, s36
	s_addc_u32 s37, s43, s37
	s_waitcnt vmcnt(28)
	v_mul_f32_e32 v36, v88, v88
	v_lshlrev_b32_e32 v34, 16, v87
	v_lshlrev_b32_e32 v32, 16, v86
	v_and_b32_e32 v33, 0xffff0000, v86
	v_add_f32_dpp v36, v36, v36 quad_perm:[1,0,3,2] row_mask:0xf bank_mask:0xf
	s_nop 1
	v_add_f32_dpp v36, v36, v36 quad_perm:[2,3,0,1] row_mask:0xf bank_mask:0xf
	s_nop 1
	v_add_f32_dpp v36, v36, v36 row_half_mirror row_mask:0xf bank_mask:0xf
	s_nop 1
	v_add_f32_dpp v36, v36, v36 row_mirror row_mask:0xf bank_mask:0xf
	ds_bpermute_b32 v37, v29, v36
	s_waitcnt lgkmcnt(0)
	v_add_f32_e32 v86, v36, v37
	s_waitcnt vmcnt(24)
	v_fmamk_f32 v35, v92, 0x3b800000, v14
	v_mul_f32_e32 v37, 0x4b800000, v35
	v_cmp_gt_f32_e32 vcc, s46, v35
	s_nop 1
	v_cndmask_b32_e32 v35, v35, v37, vcc
	v_rsq_f32_e32 v37, v35
	v_and_b32_e32 v35, 0xffff0000, v87
	v_mul_f32_e32 v36, 0x45800000, v37
	v_cndmask_b32_e32 v36, v37, v36, vcc
	v_pk_mul_f32 v[34:35], v[36:37], v[34:35] op_sel_hi:[0,1]
	v_pk_mul_f32 v[32:33], v[36:37], v[32:33] op_sel_hi:[0,1]
	global_store_dwordx4 v15, v[32:35], s[34:35] nt
	v_fmamk_f32 v86, v86, 0x3d000000, v14
	v_mul_f32_e32 v87, 0x4b800000, v86
	v_cmp_gt_f32_e32 vcc, s46, v86
	s_nop 1
	v_cndmask_b32_e32 v86, v86, v87, vcc
	v_rsq_f32_e32 v86, v86
	s_nop 0
	v_mul_f32_e32 v87, 0x45800000, v86
	v_cndmask_b32_e32 v86, v86, v87, vcc
	v_mul_f32_e32 v86, v88, v86
	s_waitcnt vmcnt(25)
	v_mul_f32_e32 v86, v86, v89
	ds_bpermute_b32 v87, v29, v86
	s_and_saveexec_b64 s[34:35], s[4:5]
	s_cbranch_execz .Lt8_end6
	s_add_u32 s16, s8, s30
	s_addc_u32 s30, s9, s31
	s_add_u32 s28, s16, s28
	s_addc_u32 s29, s30, s29
	s_lshl_b64 s[10:11], s[10:11], 6
	s_waitcnt vmcnt(25) lgkmcnt(0)
	v_mul_f32_e32 v0, v90, v87
	v_cndmask_b32_e64 v0, v0, -v0, s[6:7]
	s_waitcnt vmcnt(25)
	v_fmac_f32_e32 v0, v86, v91
	global_store_dword v16, v0, s[28:29]
	v_cvt_pk_bf16_f32 v0, v0, s0
	v_lshl_add_u64 v[86:87], v[8:9], 0, s[10:11]
	global_store_short v[86:87], v0, off
.Lt8_end6:
	s_or_b64 exec, exec, s[34:35]
	s_add_i32 s16, s47, s48
	s_add_i32 s16, s16, 56
	s_cmpk_gt_u32 s16, 0xffff
	s_mov_b64 s[30:31], -1
	s_cbranch_scc0 .Lt8r7_1246
	s_add_i32 s34, s16, 0xffff0000
	s_lshr_b32 s11, s34, 5
	s_and_b32 s10, s16, 31
	s_mul_hi_u32 s28, s11, 0x840
	s_mulk_i32 s11, 0x840
	s_or_b32 s49, s10, 0x800
	s_or_b32 s10, s11, s10
	s_add_u32 s10, s10, 0x10800
	s_mov_b32 s35, s17
	s_addc_u32 s11, s28, 0
	s_lshl_b64 s[28:29], s[34:35], 7
	s_mov_b64 s[30:31], 0

.Lt8r7_1251:
	s_add_u32 s36, s8, s36
	s_addc_u32 s37, s9, s37
	s_lshl_b64 s[34:35], s[34:35], 10
	s_add_u32 s34, s36, s34
	s_addc_u32 s35, s37, s35
	s_lshl_b64 s[36:37], s[16:17], 2
	s_add_u32 s36, s42, s36
	s_addc_u32 s37, s43, s37
	s_waitcnt vmcnt(25)
	v_mul_f32_e32 v36, v96, v96
	v_lshlrev_b32_e32 v34, 16, v95
	v_lshlrev_b32_e32 v32, 16, v94
	v_and_b32_e32 v33, 0xffff0000, v94
	v_add_f32_dpp v36, v36, v36 quad_perm:[1,0,3,2] row_mask:0xf bank_mask:0xf
	s_nop 1
	v_add_f32_dpp v36, v36, v36 quad_perm:[2,3,0,1] row_mask:0xf bank_mask:0xf
	s_nop 1
	v_add_f32_dpp v36, v36, v36 row_half_mirror row_mask:0xf bank_mask:0xf
	s_nop 1
	v_add_f32_dpp v36, v36, v36 row_mirror row_mask:0xf bank_mask:0xf
	ds_bpermute_b32 v37, v29, v36
	s_waitcnt lgkmcnt(0)
	v_add_f32_e32 v94, v36, v37
	s_waitcnt vmcnt(21)
	v_fmamk_f32 v35, v100, 0x3b800000, v14
	v_mul_f32_e32 v37, 0x4b800000, v35
	v_cmp_gt_f32_e32 vcc, s46, v35
	s_nop 1
	v_cndmask_b32_e32 v35, v35, v37, vcc
	v_rsq_f32_e32 v37, v35
	v_and_b32_e32 v35, 0xffff0000, v95
	v_mul_f32_e32 v36, 0x45800000, v37
	v_cndmask_b32_e32 v36, v37, v36, vcc
	v_pk_mul_f32 v[34:35], v[36:37], v[34:35] op_sel_hi:[0,1]
	v_pk_mul_f32 v[32:33], v[36:37], v[32:33] op_sel_hi:[0,1]
	global_store_dwordx4 v15, v[32:35], s[34:35] nt
	v_fmamk_f32 v94, v94, 0x3d000000, v14
	v_mul_f32_e32 v95, 0x4b800000, v94
	v_cmp_gt_f32_e32 vcc, s46, v94
	s_nop 1
	v_cndmask_b32_e32 v94, v94, v95, vcc
	v_rsq_f32_e32 v94, v94
	s_nop 0
	v_mul_f32_e32 v95, 0x45800000, v94
	v_cndmask_b32_e32 v94, v94, v95, vcc
	v_mul_f32_e32 v94, v96, v94
	s_waitcnt vmcnt(22)
	v_mul_f32_e32 v94, v94, v97
	ds_bpermute_b32 v95, v29, v94
	s_and_saveexec_b64 s[34:35], s[4:5]
	s_cbranch_execz .Lt8_end7
	s_add_u32 s16, s8, s30
	s_addc_u32 s30, s9, s31
	s_add_u32 s28, s16, s28
	s_addc_u32 s29, s30, s29
	s_lshl_b64 s[10:11], s[10:11], 6
	s_waitcnt vmcnt(22) lgkmcnt(0)
	v_mul_f32_e32 v0, v98, v95
	v_cndmask_b32_e64 v0, v0, -v0, s[6:7]
	s_waitcnt vmcnt(22)
	v_fmac_f32_e32 v0, v94, v99
	global_store_dword v16, v0, s[28:29]
	v_cvt_pk_bf16_f32 v0, v0, s0
	v_lshl_add_u64 v[94:95], v[8:9], 0, s[10:11]
	global_store_short v[94:95], v0, off
.Lt8_end7:
	s_or_b64 exec, exec, s[34:35]
	s_add_i32 s48, s48, 64
	s_cmpk_eq_i32 s48, 0x80
	s_cbranch_scc1 .LBB0_1235
	s_branch .LBB0_1244
